# attn unit prologue: 8 Q-fragment loads issued up front with counted vmcnt instead of 6 serialized round trips
# speedup vs baseline: 1.0077x; 1.0077x over previous
; __device__ __forceinline__ unsigned cvtpk(float lo, float hi) { unsigned r; asm volatile("v_cvt_pk_bf16_f32 %0, %1, %2" : "=v"(r) : "v"(lo), "v"(hi)); return r; }
; __device__ __forceinline__ float bflo(unsigned w) { return __uint_as_float(w << 16); }
; __device__ __forceinline__ float bfhi(unsigned w) { return __uint_as_float(w & 0xffff0000u); }
; __device__ __forceinline__ float rope_inv(int i) { return exp2f(-1.6609640474436813f * (float)i); }
; __device__ __forceinline__ void attn_unit(const bf16_t* __restrict__ Qb, bool rope_q, int tq0, const bf16_t* __restrict__ KVh, const bf16_t* __restrict__ KR,
;                                           int ctx_row0, int lat_row0, int NT, bf16_t* __restrict__ Ob, LAS unsigned char* lds, int wave_s) {
;     ...
;   { const bf16_t* Qw = Qb + (long)(wid * QBLK + r32) * 768;
; #pragma unroll
;     for (int d0 = 0; d0 < 4; ++d0) { const u32x4 w = *(const u32x4*)(Qw + d0 * 16 + hi * 8);
;       u32x4 s = {cvtpk(bflo(w.x) * C2, bfhi(w.x) * C2), cvtpk(bflo(w.y) * C2, bfhi(w.y) * C2), cvtpk(bflo(w.z) * C2, bfhi(w.z) * C2), cvtpk(bflo(w.w) * C2, bfhi(w.w) * C2)};
;       qr[d0] = __builtin_bit_cast(bf16x8, s); }
;     const int t = tq0 + wid * QBLK + r32;
; #pragma unroll
;     for (int a = 0; a < 2; ++a) {
;       const u32x4 lo = *(const u32x4*)(Qw + 64 + a * 16), hh = *(const u32x4*)(Qw + 64 + a * 16 + 8);
;       const float pos = (float)(a == 0 ? (t >> 6) : (t & 63)); float ov[8];
; #pragma unroll
;       for (int i = 0; i < 8; ++i) { const float ang = rope_q ? pos * rope_inv(i) : 0.f, c = __cosf(ang) * C2, s = __sinf(ang) * C2;
.LBB0_500:
	s_and_b32 s8, s22, 0xffffff00
	s_and_b32 s0, s22, 0x1f00
	s_mul_i32 s2, s8, 0x600
	s_mul_hi_i32 s1, s8, 0x600
	s_add_u32 s2, s15, s2
	s_addc_u32 s1, s16, s1
	v_mov_b32_e32 v2, v1
	v_mov_b32_e32 v3, v1
	v_mov_b32_e32 v4, v1
	v_mov_b32_e32 v5, v1
	v_mov_b32_e32 v6, v1
	v_mov_b32_e32 v7, v1
	v_mov_b32_e32 v8, v1
	v_mov_b32_e32 v9, v1
	v_mov_b32_e32 v10, v1
	v_mov_b32_e32 v11, v1
	v_mov_b32_e32 v12, v1
	v_mov_b32_e32 v13, v1
	v_mov_b32_e32 v14, v1
	v_mov_b32_e32 v15, v1
	s_add_u32 s2, s2, s9
	v_mov_b32_e32 v28, v206
	v_mov_b32_e32 v0, v1
	v_mov_b64_e32 v[16:17], v[14:15]
	s_addc_u32 s3, s1, 0
	v_mov_b64_e32 v[14:15], v[12:13]
	v_mov_b64_e32 v[12:13], v[10:11]
	v_mov_b64_e32 v[10:11], v[8:9]
	v_mov_b64_e32 v[8:9], v[6:7]
	v_mov_b64_e32 v[6:7], v[4:5]
	v_mov_b64_e32 v[4:5], v[2:3]
	v_mov_b64_e32 v[2:3], v[0:1]
	v_ashrrev_i32_e32 v0, 1, v28
	s_movk_i32 s1, 0xffe0
	v_bfe_u32 v143, v28, 5, 1
	v_and_b32_e32 v130, 0xffffffe0, v0
	v_bfi_b32 v0, s1, v0, v28
	v_mov_b64_e32 v[18:19], s[2:3]
	v_mad_i64_i32 v[26:27], s[2:3], v0, s67, v[18:19]
	v_lshlrev_b32_e32 v132, 4, v143
	v_mov_b32_e32 v133, v1
	v_lshl_add_u64 v[18:19], v[26:27], 0, v[132:133]
	global_load_dwordx4 v[20:23], v[18:19], off
	global_load_dwordx4 v[222:225], v[18:19], off offset:32
	global_load_dwordx4 v[226:229], v[18:19], off offset:64
	global_load_dwordx4 v[230:233], v[18:19], off offset:96
	global_load_dwordx4 v[234:237], v[26:27], off offset:128
	global_load_dwordx4 v[240:243], v[26:27], off offset:144
	global_load_dwordx4 v[244:247], v[26:27], off offset:160
	global_load_dwordx4 v[248:251], v[26:27], off offset:176
	v_and_b32_e32 v142, 31, v28
	v_and_b32_e32 v80, 63, v28
	v_cmp_gt_u32_e64 s[2:3], 32, v80
	v_ashrrev_i32_e32 v134, 4, v28
	s_waitcnt vmcnt(7)
	v_lshlrev_b32_e32 v0, 16, v20
	v_and_b32_e32 v20, 0xffff0000, v20
	v_mul_f32_e32 v20, 0x3e16c740, v20
	v_mul_f32_e32 v0, 0x3e16c740, v0
	v_cvt_pk_bf16_f32 v82, v0, v20
	v_and_b32_e32 v20, 0xffff0000, v21
	v_lshlrev_b32_e32 v0, 16, v21
	v_mul_f32_e32 v20, 0x3e16c740, v20
	v_mul_f32_e32 v0, 0x3e16c740, v0
	v_cvt_pk_bf16_f32 v83, v0, v20
	v_and_b32_e32 v20, 0xffff0000, v22
	v_lshlrev_b32_e32 v0, 16, v22
	v_mul_f32_e32 v20, 0x3e16c740, v20
	v_mul_f32_e32 v0, 0x3e16c740, v0
	v_cvt_pk_bf16_f32 v84, v0, v20
	v_and_b32_e32 v20, 0xffff0000, v23
	v_lshlrev_b32_e32 v0, 16, v23
	v_mul_f32_e32 v20, 0x3e16c740, v20
	v_mul_f32_e32 v0, 0x3e16c740, v0
	v_cvt_pk_bf16_f32 v85, v0, v20
	s_waitcnt vmcnt(6)
	v_mov_b32_e32 v20, v222
	v_mov_b32_e32 v21, v223
	v_mov_b32_e32 v22, v224
	v_mov_b32_e32 v23, v225
	v_lshlrev_b32_e32 v0, 16, v20
	v_and_b32_e32 v20, 0xffff0000, v20
	v_mul_f32_e32 v20, 0x3e16c740, v20
	v_mul_f32_e32 v0, 0x3e16c740, v0
	v_cvt_pk_bf16_f32 v86, v0, v20
	v_and_b32_e32 v20, 0xffff0000, v21
	v_lshlrev_b32_e32 v0, 16, v21
	v_mul_f32_e32 v20, 0x3e16c740, v20
	v_mul_f32_e32 v0, 0x3e16c740, v0
	v_cvt_pk_bf16_f32 v87, v0, v20
	v_and_b32_e32 v20, 0xffff0000, v22
	v_lshlrev_b32_e32 v0, 16, v22
	v_mul_f32_e32 v20, 0x3e16c740, v20
	v_mul_f32_e32 v0, 0x3e16c740, v0
	v_cvt_pk_bf16_f32 v88, v0, v20
	v_and_b32_e32 v20, 0xffff0000, v23
	v_lshlrev_b32_e32 v0, 16, v23
	v_mul_f32_e32 v20, 0x3e16c740, v20
	v_mul_f32_e32 v0, 0x3e16c740, v0
	v_cvt_pk_bf16_f32 v89, v0, v20
	s_waitcnt vmcnt(5)
	v_mov_b32_e32 v20, v226
	v_mov_b32_e32 v21, v227
	v_mov_b32_e32 v22, v228
	v_mov_b32_e32 v23, v229
	v_lshlrev_b32_e32 v0, 16, v20
	v_and_b32_e32 v20, 0xffff0000, v20
	v_mul_f32_e32 v20, 0x3e16c740, v20
	v_mul_f32_e32 v0, 0x3e16c740, v0
	v_cvt_pk_bf16_f32 v90, v0, v20
	v_and_b32_e32 v20, 0xffff0000, v21
	v_lshlrev_b32_e32 v0, 16, v21
	v_mul_f32_e32 v20, 0x3e16c740, v20
	v_mul_f32_e32 v0, 0x3e16c740, v0
	v_cvt_pk_bf16_f32 v91, v0, v20
	v_and_b32_e32 v20, 0xffff0000, v22
	v_lshlrev_b32_e32 v0, 16, v22
	v_mul_f32_e32 v20, 0x3e16c740, v20
	v_mul_f32_e32 v0, 0x3e16c740, v0
	v_cvt_pk_bf16_f32 v92, v0, v20
	v_and_b32_e32 v20, 0xffff0000, v23
	v_lshlrev_b32_e32 v0, 16, v23
	v_mul_f32_e32 v20, 0x3e16c740, v20
	v_mul_f32_e32 v0, 0x3e16c740, v0
	v_cvt_pk_bf16_f32 v93, v0, v20
	s_waitcnt vmcnt(4)
	v_mov_b32_e32 v18, v230
	v_mov_b32_e32 v19, v231
	v_mov_b32_e32 v20, v232
	v_mov_b32_e32 v21, v233
	v_lshlrev_b32_e32 v0, 16, v18
	v_and_b32_e32 v18, 0xffff0000, v18
	v_mul_f32_e32 v18, 0x3e16c740, v18
	v_mul_f32_e32 v0, 0x3e16c740, v0
	v_cvt_pk_bf16_f32 v94, v0, v18
	v_and_b32_e32 v18, 0xffff0000, v19
	v_lshlrev_b32_e32 v0, 16, v19
	v_mul_f32_e32 v18, 0x3e16c740, v18
	v_mul_f32_e32 v0, 0x3e16c740, v0
	v_cvt_pk_bf16_f32 v95, v0, v18
	v_and_b32_e32 v18, 0xffff0000, v20
	v_lshlrev_b32_e32 v0, 16, v20
	v_mul_f32_e32 v18, 0x3e16c740, v18
	v_mul_f32_e32 v0, 0x3e16c740, v0
	v_cvt_pk_bf16_f32 v96, v0, v18
	v_and_b32_e32 v18, 0xffff0000, v21
	v_lshlrev_b32_e32 v0, 16, v21
	v_mul_f32_e32 v18, 0x3e16c740, v18
	v_mul_f32_e32 v0, 0x3e16c740, v0
	v_cvt_pk_bf16_f32 v97, v0, v18
	s_waitcnt vmcnt(2)
	v_mov_b32_e32 v18, v234
	v_mov_b32_e32 v19, v235
	v_mov_b32_e32 v20, v236
	v_mov_b32_e32 v21, v237
	v_mov_b32_e32 v22, v240
	v_mov_b32_e32 v23, v241
	v_mov_b32_e32 v24, v242
	v_mov_b32_e32 v25, v243
	v_or_b32_e32 v0, s0, v142
	v_add_u32_e32 v0, v0, v130
	v_ashrrev_i32_e32 v29, 6, v0
	v_cvt_f32_i32_e32 v36, v29
	v_and_b32_e32 v0, 63, v0
	v_cvt_f32_ubyte0_e32 v0, v0
	v_mul_f32_e32 v29, 0.15915494, v36
	v_cos_f32_e32 v30, v29
	v_sin_f32_e32 v31, v29
	s_waitcnt vmcnt(1)
	v_lshlrev_b32_e32 v32, 16, v18
	v_pk_mul_f32 v[30:31], v[30:31], s[52:53] op_sel_hi:[1,0]
	s_waitcnt vmcnt(0)
; __device__ __forceinline__ unsigned cvtpk(float lo, float hi) { unsigned r; asm volatile("v_cvt_pk_bf16_f32 %0, %1, %2" : "=v"(r) : "v"(lo), "v"(hi)); return r; }
; __device__ __forceinline__ float bflo(unsigned w) { return __uint_as_float(w << 16); }
; __device__ __forceinline__ float bfhi(unsigned w) { return __uint_as_float(w & 0xffff0000u); }
; __device__ __forceinline__ float rope_inv(int i) { return exp2f(-1.6609640474436813f * (float)i); }
; __device__ __forceinline__ void attn_unit(const bf16_t* __restrict__ Qb, bool rope_q, int tq0, const bf16_t* __restrict__ KVh, const bf16_t* __restrict__ KR,
;                                           int ctx_row0, int lat_row0, int NT, bf16_t* __restrict__ Ob, LAS unsigned char* lds, int wave_s) {
;     ...
;     for (int a = 0; a < 2; ++a) {
;       const u32x4 lo = *(const u32x4*)(Qw + 64 + a * 16), hh = *(const u32x4*)(Qw + 64 + a * 16 + 8);
;       const float pos = (float)(a == 0 ? (t >> 6) : (t & 63)); float ov[8];
; #pragma unroll
;       for (int i = 0; i < 8; ++i) { const float ang = rope_q ? pos * rope_inv(i) : 0.f, c = __cosf(ang) * C2, s = __sinf(ang) * C2;
;         const float l = (i & 1) ? bfhi(lo[i >> 1]) : bflo(lo[i >> 1]), h = (i & 1) ? bfhi(hh[i >> 1]) : bflo(hh[i >> 1]);
;         ov[i] = hi ? (h * c + l * s) : (l * c - h * s); }
;       u32x4 w = {cvtpk(ov[0], ov[1]), cvtpk(ov[2], ov[3]), cvtpk(ov[4], ov[5]), cvtpk(ov[6], ov[7])}; qr[4 + a] = __builtin_bit_cast(bf16x8, w);
	v_lshlrev_b32_e32 v33, 16, v22
	v_pk_mul_f32 v[34:35], v[30:31], v[32:33] op_sel:[1,0] op_sel_hi:[0,1]
	v_pk_mul_f32 v[30:31], v[30:31], v[32:33]
	v_add_f32_e32 v29, v34, v35
	v_sub_f32_e32 v30, v30, v31
	v_cndmask_b32_e64 v29, v29, v30, s[2:3]
	v_mul_f32_e32 v30, 0x3ea1e89b, v36
	v_mul_f32_e32 v31, 0.15915494, v30
	v_cos_f32_e32 v30, v31
	v_sin_f32_e32 v31, v31
	v_and_b32_e32 v33, 0xffff0000, v22
	v_and_b32_e32 v32, 0xffff0000, v18
	v_pk_mul_f32 v[30:31], v[30:31], s[52:53] op_sel_hi:[1,0]
	s_nop 0
	v_pk_mul_f32 v[34:35], v[30:31], v[32:33] op_sel:[1,0] op_sel_hi:[0,1]
	v_pk_mul_f32 v[30:31], v[30:31], v[32:33]
	v_add_f32_e32 v18, v34, v35
	v_sub_f32_e32 v22, v30, v31
	v_cndmask_b32_e64 v18, v18, v22, s[2:3]
	v_mul_f32_e32 v22, 0x3dcccccd, v36
	v_mul_f32_e32 v22, 0.15915494, v22
	v_cos_f32_e32 v30, v22
	v_sin_f32_e32 v31, v22
	v_lshlrev_b32_e32 v33, 16, v23
	v_lshlrev_b32_e32 v32, 16, v19
	v_cvt_pk_bf16_f32 v98, v29, v18
	v_pk_mul_f32 v[30:31], v[30:31], s[52:53] op_sel_hi:[1,0]
	s_nop 0
	v_pk_mul_f32 v[34:35], v[30:31], v[32:33] op_sel:[1,0] op_sel_hi:[0,1]
	v_pk_mul_f32 v[30:31], v[30:31], v[32:33]
	v_add_f32_e32 v22, v34, v35
	v_sub_f32_e32 v30, v30, v31
	v_cndmask_b32_e64 v22, v22, v30, s[2:3]
	v_mul_f32_e32 v30, 0x3d0186e3, v36
	v_mul_f32_e32 v31, 0.15915494, v30
	v_cos_f32_e32 v30, v31
	v_sin_f32_e32 v31, v31
	v_and_b32_e32 v33, 0xffff0000, v23
	v_and_b32_e32 v32, 0xffff0000, v19
	v_pk_mul_f32 v[30:31], v[30:31], s[52:53] op_sel_hi:[1,0]
	s_nop 0
	v_pk_mul_f32 v[34:35], v[30:31], v[32:33] op_sel:[1,0] op_sel_hi:[0,1]
	v_pk_mul_f32 v[30:31], v[30:31], v[32:33]
	v_add_f32_e32 v19, v34, v35
	v_sub_f32_e32 v23, v30, v31
	v_cndmask_b32_e64 v19, v19, v23, s[2:3]
	v_mul_f32_e32 v23, 0x3c23d70b, v36
	v_mul_f32_e32 v23, 0.15915494, v23
	v_cos_f32_e32 v30, v23
	v_sin_f32_e32 v31, v23
	v_lshlrev_b32_e32 v33, 16, v24
	v_lshlrev_b32_e32 v32, 16, v20
	v_cvt_pk_bf16_f32 v99, v22, v19
	v_pk_mul_f32 v[30:31], v[30:31], s[52:53] op_sel_hi:[1,0]
	s_nop 0
	v_pk_mul_f32 v[34:35], v[30:31], v[32:33] op_sel:[1,0] op_sel_hi:[0,1]
	v_pk_mul_f32 v[30:31], v[30:31], v[32:33]
	v_add_f32_e32 v23, v34, v35
	v_sub_f32_e32 v30, v30, v31
	v_cndmask_b32_e64 v23, v23, v30, s[2:3]
	v_mul_f32_e32 v30, 0x3b4f3e39, v36
	v_mul_f32_e32 v31, 0.15915494, v30
	v_cos_f32_e32 v30, v31
	v_sin_f32_e32 v31, v31
	v_and_b32_e32 v33, 0xffff0000, v24
	v_and_b32_e32 v32, 0xffff0000, v20
	v_pk_mul_f32 v[30:31], v[30:31], s[52:53] op_sel_hi:[1,0]
	s_nop 0
	v_pk_mul_f32 v[34:35], v[30:31], v[32:33] op_sel:[1,0] op_sel_hi:[0,1]
	v_pk_mul_f32 v[30:31], v[30:31], v[32:33]
	v_add_f32_e32 v20, v34, v35
	v_sub_f32_e32 v24, v30, v31
	v_cndmask_b32_e64 v37, v20, v24, s[2:3]
	v_mul_f32_e32 v20, 0x3a831270, v36
	v_mul_f32_e32 v20, 0.15915494, v20
	v_cos_f32_e32 v30, v20
	v_sin_f32_e32 v31, v20
	v_lshlrev_b32_e32 v33, 16, v25
	v_lshlrev_b32_e32 v32, 16, v21
	v_and_b32_e32 v25, 0xffff0000, v25
	v_pk_mul_f32 v[30:31], v[30:31], s[52:53] op_sel_hi:[1,0]
	v_cvt_pk_bf16_f32 v100, v23, v37
	s_nop 0
	v_pk_mul_f32 v[34:35], v[30:31], v[32:33] op_sel:[1,0] op_sel_hi:[0,1]
	v_pk_mul_f32 v[30:31], v[30:31], v[32:33]
	v_add_f32_e32 v20, v34, v35
	v_sub_f32_e32 v24, v30, v31
	v_cndmask_b32_e64 v32, v20, v24, s[2:3]
	v_mul_f32_e32 v20, 0x39a5cb61, v36
	v_mul_f32_e32 v20, 0.15915494, v20
	v_cos_f32_e32 v30, v20
	v_sin_f32_e32 v31, v20
	v_and_b32_e32 v24, 0xffff0000, v21
	v_pk_mul_f32 v[30:31], v[30:31], s[52:53] op_sel_hi:[1,0]
	s_nop 0
	v_pk_mul_f32 v[20:21], v[30:31], v[24:25] op_sel:[1,0] op_sel_hi:[0,1]
	v_add_f32_e32 v33, v20, v21
	v_pk_mul_f32 v[20:21], v[30:31], v[24:25]
	s_nop 0
	v_sub_f32_e32 v20, v20, v21
	v_cndmask_b32_e64 v20, v33, v20, s[2:3]
	v_cvt_pk_bf16_f32 v101, v32, v20
	s_waitcnt vmcnt(0)
	v_mov_b32_e32 v18, v244
	v_mov_b32_e32 v19, v245
	v_mov_b32_e32 v20, v246
	v_mov_b32_e32 v21, v247
	v_mov_b32_e32 v22, v248
	v_mov_b32_e32 v23, v249
	v_mov_b32_e32 v24, v250
	v_mov_b32_e32 v25, v251
	v_mul_f32_e32 v27, 0.15915494, v0
	v_cos_f32_e32 v26, v27
	v_sin_f32_e32 v27, v27
	s_waitcnt vmcnt(1)
	v_lshlrev_b32_e32 v30, 16, v18
	v_pk_mul_f32 v[26:27], v[26:27], s[52:53] op_sel_hi:[1,0]
	s_waitcnt vmcnt(0)
; __device__ __forceinline__ unsigned cvtpk(float lo, float hi) { unsigned r; asm volatile("v_cvt_pk_bf16_f32 %0, %1, %2" : "=v"(r) : "v"(lo), "v"(hi)); return r; }
; __device__ __forceinline__ float bflo(unsigned w) { return __uint_as_float(w << 16); }
; __device__ __forceinline__ float bfhi(unsigned w) { return __uint_as_float(w & 0xffff0000u); }
; __device__ __forceinline__ float rope_inv(int i) { return exp2f(-1.6609640474436813f * (float)i); }
; __device__ __forceinline__ int v_st(int k, int c) { const int kk = (k & ~0xC) | ((k & 4) << 1) | ((k & 8) >> 1); return ((kk >> 3) * 4 + (c >> 5)) * 512 + ((kk & 7) * 32 + (c & 31)) * 2; }
; __device__ __forceinline__ void attn_unit(const bf16_t* __restrict__ Qb, bool rope_q, int tq0, const bf16_t* __restrict__ KVh, const bf16_t* __restrict__ KR,
;                                           int ctx_row0, int lat_row0, int NT, bf16_t* __restrict__ Ob, LAS unsigned char* lds, int wave_s) {
;     ...
;     for (int a = 0; a < 2; ++a) {
;       const u32x4 lo = *(const u32x4*)(Qw + 64 + a * 16), hh = *(const u32x4*)(Qw + 64 + a * 16 + 8);
;       const float pos = (float)(a == 0 ? (t >> 6) : (t & 63)); float ov[8];
; #pragma unroll
;       for (int i = 0; i < 8; ++i) { const float ang = rope_q ? pos * rope_inv(i) : 0.f, c = __cosf(ang) * C2, s = __sinf(ang) * C2;
;         const float l = (i & 1) ? bfhi(lo[i >> 1]) : bflo(lo[i >> 1]), h = (i & 1) ? bfhi(hh[i >> 1]) : bflo(hh[i >> 1]);
;         ov[i] = hi ? (h * c + l * s) : (l * c - h * s); }
;       u32x4 w = {cvtpk(ov[0], ov[1]), cvtpk(ov[2], ov[3]), cvtpk(ov[4], ov[5]), cvtpk(ov[6], ov[7])}; qr[4 + a] = __builtin_bit_cast(bf16x8, w);
;     }
;   }
;   const int sr = tid >> 4, sc = (tid & 15) * 8, rr = (tid & 255) >> 2, rc = (tid & 3) * 8;
;   const int st0 = (sc < 64) ? OFF_K + KSWZ(sr, sc * 2) : OFF_V + v_st(sr, sc - 64);
;   const int st1 = (sc < 64) ? OFF_K + KSWZ(32 + sr, sc * 2) : OFF_V + v_st(32 + sr, sc - 64);
	v_lshlrev_b32_e32 v31, 16, v22
	v_pk_mul_f32 v[32:33], v[26:27], v[30:31] op_sel:[1,0] op_sel_hi:[0,1]
	v_pk_mul_f32 v[26:27], v[26:27], v[30:31]
	v_add_f32_e32 v29, v32, v33
	v_sub_f32_e32 v26, v26, v27
	v_cndmask_b32_e64 v29, v29, v26, s[2:3]
	v_mul_f32_e32 v26, 0x3ea1e89b, v0
	v_mul_f32_e32 v27, 0.15915494, v26
	v_cos_f32_e32 v26, v27
	v_sin_f32_e32 v27, v27
	v_and_b32_e32 v31, 0xffff0000, v22
	v_and_b32_e32 v30, 0xffff0000, v18
	v_pk_mul_f32 v[26:27], v[26:27], s[52:53] op_sel_hi:[1,0]
	s_nop 0
	v_pk_mul_f32 v[32:33], v[26:27], v[30:31] op_sel:[1,0] op_sel_hi:[0,1]
	v_pk_mul_f32 v[26:27], v[26:27], v[30:31]
	v_add_f32_e32 v18, v32, v33
	v_sub_f32_e32 v22, v26, v27
	v_cndmask_b32_e64 v34, v18, v22, s[2:3]
	v_mul_f32_e32 v18, 0x3dcccccd, v0
	v_mul_f32_e32 v18, 0.15915494, v18
	v_cos_f32_e32 v26, v18
	v_sin_f32_e32 v27, v18
	v_lshlrev_b32_e32 v31, 16, v23
	v_lshlrev_b32_e32 v30, 16, v19
	v_and_b32_e32 v23, 0xffff0000, v23
	v_pk_mul_f32 v[26:27], v[26:27], s[52:53] op_sel_hi:[1,0]
	v_cvt_pk_bf16_f32 v102, v29, v34
	s_nop 0
	v_pk_mul_f32 v[32:33], v[26:27], v[30:31] op_sel:[1,0] op_sel_hi:[0,1]
	v_pk_mul_f32 v[26:27], v[26:27], v[30:31]
	v_add_f32_e32 v18, v32, v33
	v_sub_f32_e32 v22, v26, v27
	v_cndmask_b32_e64 v30, v18, v22, s[2:3]
	v_mul_f32_e32 v18, 0x3d0186e3, v0
	v_mul_f32_e32 v18, 0.15915494, v18
	v_cos_f32_e32 v26, v18
	v_sin_f32_e32 v27, v18
	v_and_b32_e32 v22, 0xffff0000, v19
	v_pk_mul_f32 v[26:27], v[26:27], s[52:53] op_sel_hi:[1,0]
	s_nop 0
	v_pk_mul_f32 v[18:19], v[26:27], v[22:23] op_sel:[1,0] op_sel_hi:[0,1]
	v_add_f32_e32 v31, v18, v19
	v_pk_mul_f32 v[18:19], v[26:27], v[22:23]
	v_lshlrev_b32_e32 v23, 16, v24
	v_sub_f32_e32 v18, v18, v19
	v_cndmask_b32_e64 v31, v31, v18, s[2:3]
	v_mul_f32_e32 v18, 0x3c23d70b, v0
	v_mul_f32_e32 v19, 0.15915494, v18
	v_cos_f32_e32 v18, v19
	v_sin_f32_e32 v19, v19
	v_lshlrev_b32_e32 v22, 16, v20
	v_cvt_pk_bf16_f32 v103, v30, v31
	v_pk_mul_f32 v[18:19], v[18:19], s[52:53] op_sel_hi:[1,0]
	s_nop 0
	v_pk_mul_f32 v[26:27], v[18:19], v[22:23] op_sel:[1,0] op_sel_hi:[0,1]
	v_pk_mul_f32 v[18:19], v[18:19], v[22:23]
	v_add_f32_e32 v26, v26, v27
	v_sub_f32_e32 v18, v18, v19
	v_cndmask_b32_e64 v32, v26, v18, s[2:3]
	v_mul_f32_e32 v18, 0x3b4f3e39, v0
	v_mul_f32_e32 v19, 0.15915494, v18
	v_cos_f32_e32 v18, v19
	v_sin_f32_e32 v19, v19
	v_and_b32_e32 v23, 0xffff0000, v24
	v_and_b32_e32 v22, 0xffff0000, v20
	v_pk_mul_f32 v[18:19], v[18:19], s[52:53] op_sel_hi:[1,0]
	s_nop 0
	v_pk_mul_f32 v[26:27], v[18:19], v[22:23] op_sel:[1,0] op_sel_hi:[0,1]
	v_pk_mul_f32 v[18:19], v[18:19], v[22:23]
	v_add_f32_e32 v20, v26, v27
	v_sub_f32_e32 v18, v18, v19
	v_cndmask_b32_e64 v24, v20, v18, s[2:3]
	v_mul_f32_e32 v18, 0x3a831270, v0
	v_mul_f32_e32 v19, 0.15915494, v18
	v_cos_f32_e32 v18, v19
	v_sin_f32_e32 v19, v19
	v_lshlrev_b32_e32 v23, 16, v25
	v_lshlrev_b32_e32 v22, 16, v21
	v_mul_f32_e32 v0, 0x39a5cb61, v0
	v_pk_mul_f32 v[18:19], v[18:19], s[52:53] op_sel_hi:[1,0]
	v_mul_f32_e32 v0, 0.15915494, v0
	v_pk_mul_f32 v[26:27], v[18:19], v[22:23] op_sel:[1,0] op_sel_hi:[0,1]
	v_pk_mul_f32 v[18:19], v[18:19], v[22:23]
	v_add_f32_e32 v20, v26, v27
	v_sub_f32_e32 v18, v18, v19
	v_cndmask_b32_e64 v26, v20, v18, s[2:3]
	v_cos_f32_e32 v18, v0
	v_sin_f32_e32 v19, v0
	v_and_b32_e32 v23, 0xffff0000, v25
	v_and_b32_e32 v22, 0xffff0000, v21
	v_cvt_pk_bf16_f32 v104, v32, v24
	v_pk_mul_f32 v[18:19], v[18:19], s[52:53] op_sel_hi:[1,0]
	s_nop 0
	v_pk_mul_f32 v[20:21], v[18:19], v[22:23] op_sel:[1,0] op_sel_hi:[0,1]
	v_pk_mul_f32 v[18:19], v[18:19], v[22:23]
	v_add_f32_e32 v0, v20, v21
	v_sub_f32_e32 v18, v18, v19
	v_cndmask_b32_e64 v0, v0, v18, s[2:3]
	v_lshlrev_b32_e32 v18, 3, v28
	v_cvt_pk_bf16_f32 v105, v26, v0
	v_and_b32_e32 v0, 0x78, v18
	v_subrev_u32_e32 v21, 64, v0
	v_lshrrev_b32_e32 v20, 1, v134
	v_bfe_u32 v22, v28, 4, 2
	v_cmp_lt_u32_e32 vcc, 63, v0
	v_lshrrev_b32_e32 v19, 5, v21
	v_and_or_b32 v20, v20, 4, v22
	v_lshlrev_b32_e32 v21, 1, v21
	s_and_saveexec_b64 s[0:1], vcc
	s_xor_b64 s[0:1], exec, s[0:1]
	v_and_b32_e32 v22, 0xfffff0, v134
	v_lshlrev_b32_e32 v23, 1, v134
	v_and_or_b32 v22, v23, 8, v22
	v_lshrrev_b32_e32 v22, 1, v22
	v_and_b32_e32 v23, 48, v21
	v_add_u32_e32 v22, v22, v19
	v_lshl_or_b32 v23, v20, 6, v23
	v_lshl_or_b32 v131, v22, 9, v23
	s_or_saveexec_b64 s[0:1], s[0:1]
	v_lshlrev_b32_e32 v22, 8, v134
	v_lshlrev_b32_e32 v0, 1, v0
	v_and_b32_e32 v23, 0xf0, v28
	v_bitop3_b32 v22, v22, v0, v23 bitop3:0xf6
	s_xor_b64 exec, exec, s[0:1]
	v_add_u32_e32 v131, 0xc000, v22
	s_or_b64 exec, exec, s[0:1]
	s_and_saveexec_b64 s[0:1], vcc
	s_xor_b64 s[0:1], exec, s[0:1]
	s_cbranch_execz .LBB0_506
	v_add_u32_e32 v22, 32, v134
	v_and_b32_e32 v23, 0xfffff0, v22
	v_lshlrev_b32_e32 v22, 1, v22
	v_and_or_b32 v22, v22, 8, v23
	v_lshrrev_b32_e32 v22, 1, v22
	v_and_b32_e32 v21, 48, v21
	v_add_u32_e32 v19, v22, v19
	v_lshl_or_b32 v20, v20, 6, v21
	v_lshl_or_b32 v133, v19, 9, v20
	s_andn2_saveexec_b64 s[0:1], s[0:1]
	s_cbranch_execnz .LBB0_507
	s_branch .LBB0_508
